# prologue adaLN partial matvec: 32 loads in flight per batch instead of serialized vmcnt(0) round trips
# speedup vs baseline: 1.0092x; 1.0074x over previous
; DI void phase_prologue_a(char* lds, const Params& p, int bid, int nb) {
;     ...
;       float a0 = 0.f, a1 = 0.f, a2 = 0.f, a3 = 0.f, a4 = 0.f, a5 = 0.f, a6 = 0.f, a7 = 0.f;
;       const float* w = p.w_ada + ((size_t)l * 1024 + kc * 128) * 6144 + j;
; #pragma unroll 4
;       for (int k = 0; k < 128; ++k) { const float wv = w[(size_t)k * 6144];
;         a0 += sl[k] * wv; a1 += sl[128 + k] * wv; a2 += sl[256 + k] * wv; a3 += sl[384 + k] * wv; a4 += sl[512 + k] * wv; a5 += sl[640 + k] * wv; a6 += sl[768 + k] * wv; a7 += sl[896 + k] * wv; }
.Lada_batch:
	v_lshl_add_u64 v[92:93], v[58:59], 0, s[4:5]
	global_load_dword v128, v[92:93], off
	s_add_u32 s4, s4, 0x6000
	s_addc_u32 s5, s5, 0
	v_lshl_add_u64 v[94:95], v[58:59], 0, s[4:5]
	global_load_dword v129, v[94:95], off
	s_add_u32 s4, s4, 0x6000
	s_addc_u32 s5, s5, 0
	v_lshl_add_u64 v[92:93], v[58:59], 0, s[4:5]
	global_load_dword v130, v[92:93], off
	s_add_u32 s4, s4, 0x6000
	s_addc_u32 s5, s5, 0
	v_lshl_add_u64 v[94:95], v[58:59], 0, s[4:5]
	global_load_dword v131, v[94:95], off
	s_add_u32 s4, s4, 0x6000
	s_addc_u32 s5, s5, 0
	v_lshl_add_u64 v[92:93], v[58:59], 0, s[4:5]
	global_load_dword v132, v[92:93], off
	s_add_u32 s4, s4, 0x6000
	s_addc_u32 s5, s5, 0
	v_lshl_add_u64 v[94:95], v[58:59], 0, s[4:5]
	global_load_dword v133, v[94:95], off
	s_add_u32 s4, s4, 0x6000
	s_addc_u32 s5, s5, 0
	v_lshl_add_u64 v[92:93], v[58:59], 0, s[4:5]
	global_load_dword v134, v[92:93], off
	s_add_u32 s4, s4, 0x6000
	s_addc_u32 s5, s5, 0
	v_lshl_add_u64 v[94:95], v[58:59], 0, s[4:5]
	global_load_dword v135, v[94:95], off
	s_add_u32 s4, s4, 0x6000
	s_addc_u32 s5, s5, 0
	v_lshl_add_u64 v[92:93], v[58:59], 0, s[4:5]
	global_load_dword v136, v[92:93], off
	s_add_u32 s4, s4, 0x6000
	s_addc_u32 s5, s5, 0
	v_lshl_add_u64 v[94:95], v[58:59], 0, s[4:5]
	global_load_dword v137, v[94:95], off
	s_add_u32 s4, s4, 0x6000
	s_addc_u32 s5, s5, 0
	v_lshl_add_u64 v[92:93], v[58:59], 0, s[4:5]
	global_load_dword v138, v[92:93], off
	s_add_u32 s4, s4, 0x6000
	s_addc_u32 s5, s5, 0
	v_lshl_add_u64 v[94:95], v[58:59], 0, s[4:5]
	global_load_dword v139, v[94:95], off
	s_add_u32 s4, s4, 0x6000
	s_addc_u32 s5, s5, 0
	v_lshl_add_u64 v[92:93], v[58:59], 0, s[4:5]
	global_load_dword v140, v[92:93], off
	s_add_u32 s4, s4, 0x6000
	s_addc_u32 s5, s5, 0
	v_lshl_add_u64 v[94:95], v[58:59], 0, s[4:5]
	global_load_dword v141, v[94:95], off
	s_add_u32 s4, s4, 0x6000
	s_addc_u32 s5, s5, 0
	v_lshl_add_u64 v[92:93], v[58:59], 0, s[4:5]
	global_load_dword v142, v[92:93], off
	s_add_u32 s4, s4, 0x6000
	s_addc_u32 s5, s5, 0
	v_lshl_add_u64 v[94:95], v[58:59], 0, s[4:5]
	global_load_dword v143, v[94:95], off
	s_add_u32 s4, s4, 0x6000
	s_addc_u32 s5, s5, 0
	v_lshl_add_u64 v[92:93], v[58:59], 0, s[4:5]
	global_load_dword v144, v[92:93], off
	s_add_u32 s4, s4, 0x6000
	s_addc_u32 s5, s5, 0
	v_lshl_add_u64 v[94:95], v[58:59], 0, s[4:5]
	global_load_dword v145, v[94:95], off
	s_add_u32 s4, s4, 0x6000
	s_addc_u32 s5, s5, 0
	v_lshl_add_u64 v[92:93], v[58:59], 0, s[4:5]
	global_load_dword v146, v[92:93], off
	s_add_u32 s4, s4, 0x6000
	s_addc_u32 s5, s5, 0
	v_lshl_add_u64 v[94:95], v[58:59], 0, s[4:5]
	global_load_dword v147, v[94:95], off
	s_add_u32 s4, s4, 0x6000
	s_addc_u32 s5, s5, 0
	v_lshl_add_u64 v[92:93], v[58:59], 0, s[4:5]
	global_load_dword v148, v[92:93], off
	s_add_u32 s4, s4, 0x6000
	s_addc_u32 s5, s5, 0
	v_lshl_add_u64 v[94:95], v[58:59], 0, s[4:5]
	global_load_dword v149, v[94:95], off
	s_add_u32 s4, s4, 0x6000
	s_addc_u32 s5, s5, 0
	v_lshl_add_u64 v[92:93], v[58:59], 0, s[4:5]
	global_load_dword v150, v[92:93], off
	s_add_u32 s4, s4, 0x6000
	s_addc_u32 s5, s5, 0
	v_lshl_add_u64 v[94:95], v[58:59], 0, s[4:5]
	global_load_dword v151, v[94:95], off
	s_add_u32 s4, s4, 0x6000
	s_addc_u32 s5, s5, 0
	v_lshl_add_u64 v[92:93], v[58:59], 0, s[4:5]
	global_load_dword v152, v[92:93], off
	s_add_u32 s4, s4, 0x6000
	s_addc_u32 s5, s5, 0
	v_lshl_add_u64 v[94:95], v[58:59], 0, s[4:5]
	global_load_dword v153, v[94:95], off
	s_add_u32 s4, s4, 0x6000
	s_addc_u32 s5, s5, 0
	v_lshl_add_u64 v[92:93], v[58:59], 0, s[4:5]
	global_load_dword v154, v[92:93], off
	s_add_u32 s4, s4, 0x6000
	s_addc_u32 s5, s5, 0
	v_lshl_add_u64 v[94:95], v[58:59], 0, s[4:5]
	global_load_dword v155, v[94:95], off
	s_add_u32 s4, s4, 0x6000
	s_addc_u32 s5, s5, 0
	v_lshl_add_u64 v[92:93], v[58:59], 0, s[4:5]
	global_load_dword v156, v[92:93], off
	s_add_u32 s4, s4, 0x6000
	s_addc_u32 s5, s5, 0
	v_lshl_add_u64 v[94:95], v[58:59], 0, s[4:5]
	global_load_dword v157, v[94:95], off
	s_add_u32 s4, s4, 0x6000
	s_addc_u32 s5, s5, 0
	v_lshl_add_u64 v[92:93], v[58:59], 0, s[4:5]
	global_load_dword v158, v[92:93], off
	s_add_u32 s4, s4, 0x6000
	s_addc_u32 s5, s5, 0
	v_lshl_add_u64 v[94:95], v[58:59], 0, s[4:5]
	global_load_dword v159, v[94:95], off
	s_add_u32 s4, s4, 0x6000
	s_addc_u32 s5, s5, 0
	v_mov_b32_e32 v90, s46
	ds_read_b128 v[96:99], v90
	ds_read_b128 v[100:103], v90 offset:512
	ds_read_b128 v[104:107], v90 offset:1024
	ds_read_b128 v[108:111], v90 offset:1536
	ds_read_b128 v[112:115], v90 offset:2048
	ds_read_b128 v[116:119], v90 offset:2560
	ds_read_b128 v[120:123], v90 offset:3072
	ds_read_b128 v[124:127], v90 offset:3584
	s_add_i32 s46, s46, 16
	v_mov_b32_e32 v90, s46
	ds_read_b128 v[160:163], v90
	ds_read_b128 v[164:167], v90 offset:512
	ds_read_b128 v[168:171], v90 offset:1024
	ds_read_b128 v[172:175], v90 offset:1536
	ds_read_b128 v[176:179], v90 offset:2048
	ds_read_b128 v[180:183], v90 offset:2560
	ds_read_b128 v[184:187], v90 offset:3072
	ds_read_b128 v[188:191], v90 offset:3584
	s_add_i32 s46, s46, 16
	s_waitcnt lgkmcnt(8)
	s_waitcnt vmcnt(28)
; DI void phase_prologue_a(char* lds, const Params& p, int bid, int nb) {
;     ...
;       for (int k = 0; k < 128; ++k) { const float wv = w[(size_t)k * 6144];
;         a0 += sl[k] * wv; a1 += sl[128 + k] * wv; a2 += sl[256 + k] * wv; a3 += sl[384 + k] * wv; a4 += sl[512 + k] * wv; a5 += sl[640 + k] * wv; a6 += sl[768 + k] * wv; a7 += sl[896 + k] * wv; }
	v_fma_f32 v10, v128, v96, v10
	v_fma_f32 v11, v128, v100, v11
	v_fma_f32 v18, v128, v104, v18
	v_fma_f32 v19, v128, v108, v19
	v_fma_f32 v26, v128, v112, v26
	v_fma_f32 v27, v128, v116, v27
	v_fma_f32 v60, v128, v120, v60
	v_fma_f32 v61, v128, v124, v61
	v_fma_f32 v10, v129, v97, v10
	v_fma_f32 v11, v129, v101, v11
	v_fma_f32 v18, v129, v105, v18
	v_fma_f32 v19, v129, v109, v19
	v_fma_f32 v26, v129, v113, v26
	v_fma_f32 v27, v129, v117, v27
	v_fma_f32 v60, v129, v121, v60
	v_fma_f32 v61, v129, v125, v61
	v_fma_f32 v10, v130, v98, v10
	v_fma_f32 v11, v130, v102, v11
	v_fma_f32 v18, v130, v106, v18
	v_fma_f32 v19, v130, v110, v19
	v_fma_f32 v26, v130, v114, v26
	v_fma_f32 v27, v130, v118, v27
	v_fma_f32 v60, v130, v122, v60
	v_fma_f32 v61, v130, v126, v61
	v_fma_f32 v10, v131, v99, v10
	v_fma_f32 v11, v131, v103, v11
	v_fma_f32 v18, v131, v107, v18
	v_fma_f32 v19, v131, v111, v19
	v_fma_f32 v26, v131, v115, v26
	v_fma_f32 v27, v131, v119, v27
	v_fma_f32 v60, v131, v123, v60
	v_fma_f32 v61, v131, v127, v61
	v_mov_b32_e32 v90, s46
	ds_read_b128 v[96:99], v90
	ds_read_b128 v[100:103], v90 offset:512
	ds_read_b128 v[104:107], v90 offset:1024
	ds_read_b128 v[108:111], v90 offset:1536
	ds_read_b128 v[112:115], v90 offset:2048
	ds_read_b128 v[116:119], v90 offset:2560
	ds_read_b128 v[120:123], v90 offset:3072
	ds_read_b128 v[124:127], v90 offset:3584
	s_add_i32 s46, s46, 16
	s_waitcnt lgkmcnt(8)
	s_waitcnt vmcnt(24)
	v_fma_f32 v10, v132, v160, v10
	v_fma_f32 v11, v132, v164, v11
	v_fma_f32 v18, v132, v168, v18
	v_fma_f32 v19, v132, v172, v19
	v_fma_f32 v26, v132, v176, v26
	v_fma_f32 v27, v132, v180, v27
	v_fma_f32 v60, v132, v184, v60
	v_fma_f32 v61, v132, v188, v61
	v_fma_f32 v10, v133, v161, v10
	v_fma_f32 v11, v133, v165, v11
	v_fma_f32 v18, v133, v169, v18
	v_fma_f32 v19, v133, v173, v19
	v_fma_f32 v26, v133, v177, v26
	v_fma_f32 v27, v133, v181, v27
	v_fma_f32 v60, v133, v185, v60
	v_fma_f32 v61, v133, v189, v61
	v_fma_f32 v10, v134, v162, v10
	v_fma_f32 v11, v134, v166, v11
	v_fma_f32 v18, v134, v170, v18
	v_fma_f32 v19, v134, v174, v19
	v_fma_f32 v26, v134, v178, v26
	v_fma_f32 v27, v134, v182, v27
	v_fma_f32 v60, v134, v186, v60
	v_fma_f32 v61, v134, v190, v61
	v_fma_f32 v10, v135, v163, v10
	v_fma_f32 v11, v135, v167, v11
	v_fma_f32 v18, v135, v171, v18
	v_fma_f32 v19, v135, v175, v19
	v_fma_f32 v26, v135, v179, v26
	v_fma_f32 v27, v135, v183, v27
	v_fma_f32 v60, v135, v187, v60
	v_fma_f32 v61, v135, v191, v61
	v_mov_b32_e32 v90, s46
	ds_read_b128 v[160:163], v90
	ds_read_b128 v[164:167], v90 offset:512
	ds_read_b128 v[168:171], v90 offset:1024
	ds_read_b128 v[172:175], v90 offset:1536
	ds_read_b128 v[176:179], v90 offset:2048
	ds_read_b128 v[180:183], v90 offset:2560
	ds_read_b128 v[184:187], v90 offset:3072
	ds_read_b128 v[188:191], v90 offset:3584
	s_add_i32 s46, s46, 16
	s_waitcnt lgkmcnt(8)
	s_waitcnt vmcnt(20)
	v_fma_f32 v10, v136, v96, v10
	v_fma_f32 v11, v136, v100, v11
	v_fma_f32 v18, v136, v104, v18
	v_fma_f32 v19, v136, v108, v19
	v_fma_f32 v26, v136, v112, v26
	v_fma_f32 v27, v136, v116, v27
	v_fma_f32 v60, v136, v120, v60
	v_fma_f32 v61, v136, v124, v61
	v_fma_f32 v10, v137, v97, v10
	v_fma_f32 v11, v137, v101, v11
	v_fma_f32 v18, v137, v105, v18
	v_fma_f32 v19, v137, v109, v19
	v_fma_f32 v26, v137, v113, v26
	v_fma_f32 v27, v137, v117, v27
	v_fma_f32 v60, v137, v121, v60
	v_fma_f32 v61, v137, v125, v61
	v_fma_f32 v10, v138, v98, v10
	v_fma_f32 v11, v138, v102, v11
	v_fma_f32 v18, v138, v106, v18
	v_fma_f32 v19, v138, v110, v19
	v_fma_f32 v26, v138, v114, v26
	v_fma_f32 v27, v138, v118, v27
	v_fma_f32 v60, v138, v122, v60
	v_fma_f32 v61, v138, v126, v61
	v_fma_f32 v10, v139, v99, v10
	v_fma_f32 v11, v139, v103, v11
	v_fma_f32 v18, v139, v107, v18
	v_fma_f32 v19, v139, v111, v19
	v_fma_f32 v26, v139, v115, v26
	v_fma_f32 v27, v139, v119, v27
	v_fma_f32 v60, v139, v123, v60
	v_fma_f32 v61, v139, v127, v61
	v_mov_b32_e32 v90, s46
	ds_read_b128 v[96:99], v90
	ds_read_b128 v[100:103], v90 offset:512
	ds_read_b128 v[104:107], v90 offset:1024
	ds_read_b128 v[108:111], v90 offset:1536
	ds_read_b128 v[112:115], v90 offset:2048
	ds_read_b128 v[116:119], v90 offset:2560
	ds_read_b128 v[120:123], v90 offset:3072
	ds_read_b128 v[124:127], v90 offset:3584
	s_add_i32 s46, s46, 16
	s_waitcnt lgkmcnt(8)
	s_waitcnt vmcnt(16)
	v_fma_f32 v10, v140, v160, v10
	v_fma_f32 v11, v140, v164, v11
	v_fma_f32 v18, v140, v168, v18
	v_fma_f32 v19, v140, v172, v19
	v_fma_f32 v26, v140, v176, v26
	v_fma_f32 v27, v140, v180, v27
	v_fma_f32 v60, v140, v184, v60
	v_fma_f32 v61, v140, v188, v61
	v_fma_f32 v10, v141, v161, v10
	v_fma_f32 v11, v141, v165, v11
	v_fma_f32 v18, v141, v169, v18
	v_fma_f32 v19, v141, v173, v19
	v_fma_f32 v26, v141, v177, v26
	v_fma_f32 v27, v141, v181, v27
	v_fma_f32 v60, v141, v185, v60
	v_fma_f32 v61, v141, v189, v61
	v_fma_f32 v10, v142, v162, v10
	v_fma_f32 v11, v142, v166, v11
	v_fma_f32 v18, v142, v170, v18
	v_fma_f32 v19, v142, v174, v19
	v_fma_f32 v26, v142, v178, v26
	v_fma_f32 v27, v142, v182, v27
	v_fma_f32 v60, v142, v186, v60
	v_fma_f32 v61, v142, v190, v61
	v_fma_f32 v10, v143, v163, v10
	v_fma_f32 v11, v143, v167, v11
	v_fma_f32 v18, v143, v171, v18
	v_fma_f32 v19, v143, v175, v19
	v_fma_f32 v26, v143, v179, v26
	v_fma_f32 v27, v143, v183, v27
	v_fma_f32 v60, v143, v187, v60
	v_fma_f32 v61, v143, v191, v61
	v_mov_b32_e32 v90, s46
	ds_read_b128 v[160:163], v90
	ds_read_b128 v[164:167], v90 offset:512
	ds_read_b128 v[168:171], v90 offset:1024
	ds_read_b128 v[172:175], v90 offset:1536
	ds_read_b128 v[176:179], v90 offset:2048
	ds_read_b128 v[180:183], v90 offset:2560
	ds_read_b128 v[184:187], v90 offset:3072
	ds_read_b128 v[188:191], v90 offset:3584
	s_add_i32 s46, s46, 16
	s_waitcnt lgkmcnt(8)
; DI void phase_prologue_a(char* lds, const Params& p, int bid, int nb) {
;     ...
;       for (int k = 0; k < 128; ++k) { const float wv = w[(size_t)k * 6144];
;         a0 += sl[k] * wv; a1 += sl[128 + k] * wv; a2 += sl[256 + k] * wv; a3 += sl[384 + k] * wv; a4 += sl[512 + k] * wv; a5 += sl[640 + k] * wv; a6 += sl[768 + k] * wv; a7 += sl[896 + k] * wv; }
;       float* d = p.modp + ((size_t)(kc * 2 + l) * 8) * 6144 + j;
;       d[0] = a0; d[6144] = a1; d[2 * 6144] = a2; d[3 * 6144] = a3; d[4 * 6144] = a4; d[5 * 6144] = a5; d[6 * 6144] = a6; d[7 * 6144] = a7;
	s_waitcnt vmcnt(12)
	v_fma_f32 v10, v144, v96, v10
	v_fma_f32 v11, v144, v100, v11
	v_fma_f32 v18, v144, v104, v18
	v_fma_f32 v19, v144, v108, v19
	v_fma_f32 v26, v144, v112, v26
	v_fma_f32 v27, v144, v116, v27
	v_fma_f32 v60, v144, v120, v60
	v_fma_f32 v61, v144, v124, v61
	v_fma_f32 v10, v145, v97, v10
	v_fma_f32 v11, v145, v101, v11
	v_fma_f32 v18, v145, v105, v18
	v_fma_f32 v19, v145, v109, v19
	v_fma_f32 v26, v145, v113, v26
	v_fma_f32 v27, v145, v117, v27
	v_fma_f32 v60, v145, v121, v60
	v_fma_f32 v61, v145, v125, v61
	v_fma_f32 v10, v146, v98, v10
	v_fma_f32 v11, v146, v102, v11
	v_fma_f32 v18, v146, v106, v18
	v_fma_f32 v19, v146, v110, v19
	v_fma_f32 v26, v146, v114, v26
	v_fma_f32 v27, v146, v118, v27
	v_fma_f32 v60, v146, v122, v60
	v_fma_f32 v61, v146, v126, v61
	v_fma_f32 v10, v147, v99, v10
	v_fma_f32 v11, v147, v103, v11
	v_fma_f32 v18, v147, v107, v18
	v_fma_f32 v19, v147, v111, v19
	v_fma_f32 v26, v147, v115, v26
	v_fma_f32 v27, v147, v119, v27
	v_fma_f32 v60, v147, v123, v60
	v_fma_f32 v61, v147, v127, v61
	v_mov_b32_e32 v90, s46
	ds_read_b128 v[96:99], v90
	ds_read_b128 v[100:103], v90 offset:512
	ds_read_b128 v[104:107], v90 offset:1024
	ds_read_b128 v[108:111], v90 offset:1536
	ds_read_b128 v[112:115], v90 offset:2048
	ds_read_b128 v[116:119], v90 offset:2560
	ds_read_b128 v[120:123], v90 offset:3072
	ds_read_b128 v[124:127], v90 offset:3584
	s_add_i32 s46, s46, 16
	s_waitcnt lgkmcnt(8)
	s_waitcnt vmcnt(8)
	v_fma_f32 v10, v148, v160, v10
	v_fma_f32 v11, v148, v164, v11
	v_fma_f32 v18, v148, v168, v18
	v_fma_f32 v19, v148, v172, v19
	v_fma_f32 v26, v148, v176, v26
	v_fma_f32 v27, v148, v180, v27
	v_fma_f32 v60, v148, v184, v60
	v_fma_f32 v61, v148, v188, v61
	v_fma_f32 v10, v149, v161, v10
	v_fma_f32 v11, v149, v165, v11
	v_fma_f32 v18, v149, v169, v18
	v_fma_f32 v19, v149, v173, v19
	v_fma_f32 v26, v149, v177, v26
	v_fma_f32 v27, v149, v181, v27
	v_fma_f32 v60, v149, v185, v60
	v_fma_f32 v61, v149, v189, v61
	v_fma_f32 v10, v150, v162, v10
	v_fma_f32 v11, v150, v166, v11
	v_fma_f32 v18, v150, v170, v18
	v_fma_f32 v19, v150, v174, v19
	v_fma_f32 v26, v150, v178, v26
	v_fma_f32 v27, v150, v182, v27
	v_fma_f32 v60, v150, v186, v60
	v_fma_f32 v61, v150, v190, v61
	v_fma_f32 v10, v151, v163, v10
	v_fma_f32 v11, v151, v167, v11
	v_fma_f32 v18, v151, v171, v18
	v_fma_f32 v19, v151, v175, v19
	v_fma_f32 v26, v151, v179, v26
	v_fma_f32 v27, v151, v183, v27
	v_fma_f32 v60, v151, v187, v60
	v_fma_f32 v61, v151, v191, v61
	v_mov_b32_e32 v90, s46
	ds_read_b128 v[160:163], v90
	ds_read_b128 v[164:167], v90 offset:512
	ds_read_b128 v[168:171], v90 offset:1024
	ds_read_b128 v[172:175], v90 offset:1536
	ds_read_b128 v[176:179], v90 offset:2048
	ds_read_b128 v[180:183], v90 offset:2560
	ds_read_b128 v[184:187], v90 offset:3072
	ds_read_b128 v[188:191], v90 offset:3584
	s_add_i32 s46, s46, 16
	s_waitcnt lgkmcnt(8)
	s_waitcnt vmcnt(4)
	v_fma_f32 v10, v152, v96, v10
	v_fma_f32 v11, v152, v100, v11
	v_fma_f32 v18, v152, v104, v18
	v_fma_f32 v19, v152, v108, v19
	v_fma_f32 v26, v152, v112, v26
	v_fma_f32 v27, v152, v116, v27
	v_fma_f32 v60, v152, v120, v60
	v_fma_f32 v61, v152, v124, v61
	v_fma_f32 v10, v153, v97, v10
	v_fma_f32 v11, v153, v101, v11
	v_fma_f32 v18, v153, v105, v18
	v_fma_f32 v19, v153, v109, v19
	v_fma_f32 v26, v153, v113, v26
	v_fma_f32 v27, v153, v117, v27
	v_fma_f32 v60, v153, v121, v60
	v_fma_f32 v61, v153, v125, v61
	v_fma_f32 v10, v154, v98, v10
	v_fma_f32 v11, v154, v102, v11
	v_fma_f32 v18, v154, v106, v18
	v_fma_f32 v19, v154, v110, v19
	v_fma_f32 v26, v154, v114, v26
	v_fma_f32 v27, v154, v118, v27
	v_fma_f32 v60, v154, v122, v60
	v_fma_f32 v61, v154, v126, v61
	v_fma_f32 v10, v155, v99, v10
	v_fma_f32 v11, v155, v103, v11
	v_fma_f32 v18, v155, v107, v18
	v_fma_f32 v19, v155, v111, v19
	v_fma_f32 v26, v155, v115, v26
	v_fma_f32 v27, v155, v119, v27
	v_fma_f32 v60, v155, v123, v60
	v_fma_f32 v61, v155, v127, v61
	s_waitcnt lgkmcnt(0)
	s_waitcnt vmcnt(0)
	v_fma_f32 v10, v156, v160, v10
	v_fma_f32 v11, v156, v164, v11
	v_fma_f32 v18, v156, v168, v18
	v_fma_f32 v19, v156, v172, v19
	v_fma_f32 v26, v156, v176, v26
	v_fma_f32 v27, v156, v180, v27
	v_fma_f32 v60, v156, v184, v60
	v_fma_f32 v61, v156, v188, v61
	v_fma_f32 v10, v157, v161, v10
	v_fma_f32 v11, v157, v165, v11
	v_fma_f32 v18, v157, v169, v18
	v_fma_f32 v19, v157, v173, v19
	v_fma_f32 v26, v157, v177, v26
	v_fma_f32 v27, v157, v181, v27
	v_fma_f32 v60, v157, v185, v60
	v_fma_f32 v61, v157, v189, v61
	v_fma_f32 v10, v158, v162, v10
	v_fma_f32 v11, v158, v166, v11
	v_fma_f32 v18, v158, v170, v18
	v_fma_f32 v19, v158, v174, v19
	v_fma_f32 v26, v158, v178, v26
	v_fma_f32 v27, v158, v182, v27
	v_fma_f32 v60, v158, v186, v60
	v_fma_f32 v61, v158, v190, v61
	v_fma_f32 v10, v159, v163, v10
	v_fma_f32 v11, v159, v167, v11
	v_fma_f32 v18, v159, v171, v18
	v_fma_f32 v19, v159, v175, v19
	v_fma_f32 v26, v159, v179, v26
	v_fma_f32 v27, v159, v183, v27
	v_fma_f32 v60, v159, v187, v60
	v_fma_f32 v61, v159, v191, v61
	s_cmp_eq_u32 s4, 0x300000
	s_cbranch_scc0 .Lada_batch
	s_mov_b32 s47, 0x12000
	s_lshl_b32 s4, s8, 4
	s_and_b64 s[0:1], s[0:1], exec
	s_cselect_b32 s0, 8, 0
	s_or_b32 s0, s0, s4
	v_readlane_b32 s16, v252, 17
	s_mulk_i32 s0, 0x6000
	v_readlane_b32 s22, v252, 23
	v_readlane_b32 s23, v252, 24
	s_add_u32 s0, s22, s0
	s_addc_u32 s1, s23, 0
	v_lshl_add_u64 v[2:3], v[56:57], 2, s[0:1]
	v_add_co_u32_e32 v4, vcc, 0x6000, v2
	global_store_dword v[2:3], v10, off
	s_nop 0
	v_addc_co_u32_e32 v5, vcc, 0, v3, vcc
	global_store_dword v[4:5], v11, off
	v_add_co_u32_e32 v4, vcc, 0xc000, v2
	v_readlane_b32 s17, v252, 18
	s_nop 0
	v_addc_co_u32_e32 v5, vcc, 0, v3, vcc
	global_store_dword v[4:5], v18, off
	v_add_co_u32_e32 v4, vcc, 0x12000, v2
	v_readlane_b32 s18, v252, 19
	s_nop 0
	v_addc_co_u32_e32 v5, vcc, 0, v3, vcc
	global_store_dword v[4:5], v19, off
	v_add_co_u32_e32 v4, vcc, 0x18000, v2
	v_readlane_b32 s19, v252, 20
	s_nop 0
	v_addc_co_u32_e32 v5, vcc, 0, v3, vcc
	global_store_dword v[4:5], v26, off
	v_add_co_u32_e32 v4, vcc, 0x1e000, v2
	v_readlane_b32 s20, v252, 21
	s_nop 0
	v_addc_co_u32_e32 v5, vcc, 0, v3, vcc
	global_store_dword v[4:5], v27, off
	v_add_co_u32_e32 v4, vcc, 0x24000, v2
	v_readlane_b32 s21, v252, 22
	s_nop 0
	v_addc_co_u32_e32 v5, vcc, 0, v3, vcc
	v_add_co_u32_e32 v2, vcc, 0x2a000, v2
	v_readlane_b32 s24, v252, 25
	s_nop 0
	v_addc_co_u32_e32 v3, vcc, 0, v3, vcc
	v_readlane_b32 s25, v252, 26
	v_readlane_b32 s26, v252, 27
	v_readlane_b32 s27, v252, 28
	v_readlane_b32 s28, v252, 29
	v_readlane_b32 s29, v252, 30
	v_readlane_b32 s30, v252, 31
	v_readlane_b32 s31, v252, 32
	global_store_dword v[4:5], v60, off
	global_store_dword v[2:3], v61, off
	s_barrier

; template <int MODE>
; DI void attn_unit(char* lds, const Params& p, int layer, int u) {
;     ...
;   else { const bf16_t* q = p.proj + (size_t)token * LDP + (MODE == 2 ? C_CQ : C_DQ) + h * 64 + lh * 8;
; #pragma unroll
;     for (int ks = 0; ks < NKS; ++ks) qf[ks] = *(const bf16x8*)(q + ks * 16); }
;   const bf16_t* vtbase = (MODE == 0) ? p.vta + (size_t)((b * 4 + h) * 64) * 4096 : (MODE == 1) ? p.vtb + (size_t)((b * 4 + h) * 64) * 4096 : p.vtc + (size_t)((b * 2 + (h >> 1)) * 64) * 4096;
;   float slope2 = 0.f;
;   if (MODE == 0) slope2 = exp2f(-(float)(2 * h + 1)) * LOG2E;
;   if (MODE == 3) slope2 = exp2f(-(float)(2 * h + 2)) * LOG2E * (float)dl;
;   const int srow = tid >> 3, sc = tid & 7;
;   u32x4 kr0, kr2, vr0;
;   kr2 = (u32x4){0u, 0u, 0u, 0u};
;   auto prefetch = [&](int t) __attribute__((always_inline)) {
;     const int key0 = (MODE == 3) ? q0 - 64 + 64 * t : 64 * (tlo + t);
;     if (MODE != 3) {
;       const size_t tokk = (size_t)(b * SEQ + key0 + srow);
;       const bf16_t* kp = (MODE == 0) ? p.proj + tokk * LDP + C_AK + h * 64 : (MODE == 1) ? p.knb + tokk * 256 + h * 64 : p.proj + tokk * LDP + C_CK + (h >> 1) * 64;
;       kr0 = *(const u32x4*)(kp + sc * 8);
;       if (MODE == 1) kr2 = *(const u32x4*)(p.proj + tokk * LDP + C_BKR + (sc & 3) * 8);
;       vr0 = *(const u32x4*)(vtbase + (size_t)srow * 4096 + key0 + sc * 8);
;     } else {
;       int v = key0 + srow; v = v < 0 ? 0 : (v >= L ? L - 1 : v);
;       const bf16_t* kp = p.proj + (size_t)(b * SEQ + rho + dl * v) * LDP + h * 64;
;       kr0 = *(const u32x4*)(kp + C_DK + sc * 8);
;       vr0 = *(const u32x4*)(kp + C_DV + sc * 8);
;     }
;   };
;   auto stage = [&](char* buf) __attribute__((always_inline)) {
;     char* kd = buf + srow * KST + sc * 16;
;     *(u32x4*)kd = kr0;
;     if (MODE == 1) { if (sc < 4) *(u32x4*)(buf + srow * KST + 128 + sc * 16) = kr2; }
;     if (MODE != 3) { *(u32x4*)(buf + VOFF + srow * VST + sc * 16) = vr0; }
;     else {
;       bf16_t* vd = (bf16_t*)(buf + VOFF) + srow;
; #pragma unroll
;       for (int e = 0; e < 4; ++e) { vd[(sc * 8 + 2 * e) * 72] = (bf16_t)(vr0[e] & 0xffffu); vd[(sc * 8 + 2 * e + 1) * 72] = (bf16_t)(vr0[e] >> 16); }
;     }
;   };
;   f32x16 O0 = zero16(), O1 = zero16();
;   float m = -1e30f, l = 0.f;
;   f32x16 T0 = zero16(), T1 = zero16();
;   if (MODE == 0) {
; #pragma unroll
.LBB0_580:
	s_or_b64 exec, exec, s[0:1]
	s_waitcnt lgkmcnt(0)
	s_barrier
	ds_read_b32 v0, v166
	s_movk_i32 s0, 0xbff
	s_waitcnt lgkmcnt(0)
	v_cmp_lt_i32_e32 vcc, s0, v0
	v_readfirstlane_b32 s96, v0
	s_mov_b64 s[0:1], -1
	s_cbranch_vccnz .LBB0_575
	s_cmpk_lt_i32 s96, 0x800
	s_cbranch_scc0 .LBB0_642
	s_add_i32 s0, s96, 0xfffffb00
	s_cmp_gt_u32 s0, 0xfffffbff
	s_mov_b64 s[0:1], -1
	s_cbranch_scc0 .LBB0_603
	s_cmpk_gt_u32 s96, 0x2ff
	s_cbranch_scc0 .LBB0_593
	s_add_i32 s33, s96, 0xfffffd00
	s_lshr_b32 s50, s33, 6
	s_lshl_b32 s0, s33, 8
	v_mov_b32_e32 v6, v206
	s_and_b32 s0, s0, 0xf00
	s_lshl_b32 s52, s50, 12
	s_or_b32 s0, s52, s0
	v_and_b32_e32 v11, 31, v6
	v_ashrrev_i32_e32 v0, 1, v6
	v_readlane_b32 s56, v252, 0
	v_and_b32_e32 v0, 0xffffffe0, v0
	v_or_b32_e32 v1, s0, v11
	v_readlane_b32 s64, v252, 8
	v_readlane_b32 s65, v252, 9
	v_add_u32_e32 v88, v1, v0
	v_readlane_b32 s36, v252, 36
	v_mov_b64_e32 v[0:1], s[64:65]
	v_mad_i64_i32 v[2:3], s[0:1], v88, s72, v[0:1]
	s_lshl_b32 s0, s33, 2
	s_and_b32 s0, s0, 0xc0
	s_lshl_b32 s1, s33, 1
	s_lshl_b32 s4, s0, 1
	s_and_b32 s1, s1, 64
	v_lshl_add_u64 v[2:3], v[2:3], 0, s[4:5]
	s_lshl_b32 s4, s50, 20
	s_lshl_b32 s33, s1, 13
	s_or_b32 s33, s33, s4
	v_readlane_b32 s38, v252, 38
	v_ashrrev_i32_e32 v20, 3, v6
	v_readlane_b32 s39, v252, 39
	s_add_u32 s50, s38, s33
	v_ashrrev_i32_e32 v21, 31, v20
	v_bfe_u32 v26, v6, 5, 1
	s_addc_u32 s51, s39, 0
	v_add_u32_e32 v27, s52, v20
	v_lshlrev_b32_e32 v6, 4, v6
	v_lshlrev_b64 v[24:25], 13, v[20:21]
	v_lshlrev_b32_e32 v92, 4, v26
	v_mov_b32_e32 v93, v113
	v_mad_i64_i32 v[4:5], s[52:53], v27, s72, v[0:1]
	s_lshl_b32 s4, s1, 1
	v_and_b32_e32 v22, 0x70, v6
	v_mov_b32_e32 v23, v113
	v_lshl_add_u64 v[6:7], s[50:51], 0, v[24:25]
	v_lshl_add_u64 v[2:3], v[2:3], 0, v[92:93]
	v_lshl_add_u64 v[4:5], v[4:5], 0, s[4:5]
	v_lshl_add_u64 v[6:7], v[6:7], 0, v[22:23]
	global_load_dwordx4 v[76:79], v[2:3], off offset:2816
	global_load_dwordx4 v[72:75], v[2:3], off offset:2848
	v_lshl_add_u64 v[4:5], v[4:5], 0, v[22:23]
	global_load_dwordx4 v[12:15], v[6:7], off
	global_load_dwordx4 v[16:19], v[4:5], off offset:3328
	global_load_dwordx4 v[68:71], v[2:3], off offset:2880
	global_load_dwordx4 v[64:67], v[2:3], off offset:2912
	v_add_u32_e32 v2, 64, v27
	v_mad_i64_i32 v[0:1], s[50:51], v2, s72, v[0:1]
	v_lshl_add_u64 v[0:1], v[0:1], 0, s[4:5]
	v_lshl_add_u64 v[0:1], v[0:1], 0, v[22:23]
	s_barrier
	global_load_dwordx4 v[84:87], v[0:1], off offset:3328
	global_load_dwordx4 v[80:83], v[6:7], off offset:128
	v_mad_u64_u32 v[94:95], s[50:51], v20, s73, v[22:23]
	s_add_u32 s50, s64, s4
	s_addc_u32 s51, s65, 0
	v_readlane_b32 s4, v254, 63
	v_lshl_add_u64 v[96:97], s[50:51], 0, v[22:23]
	s_add_u32 s50, s4, s33
	v_readlane_b32 s4, v255, 0
	v_or_b32_e32 v24, v24, v22
	s_addc_u32 s51, s4, 0
	v_mov_b32_e32 v0, v113
	v_mov_b32_e32 v1, v113
	v_mov_b32_e32 v2, v113
	v_mov_b32_e32 v3, v113
	v_mov_b32_e32 v4, v113
	v_mov_b32_e32 v5, v113
	v_mov_b32_e32 v6, v113
	v_mov_b32_e32 v7, v113
	v_mov_b32_e32 v8, v113
	v_mov_b32_e32 v9, v113
	v_mov_b32_e32 v10, v113
	v_lshlrev_b32_e32 v112, 3, v26
	v_mul_u32_u24_e32 v100, 0x90, v11
	v_add_u32_e32 v101, 0x80, v27
	v_lshl_add_u64 v[98:99], s[50:51], 0, v[24:25]
	v_mov_b32_e32 v11, v113
	s_mov_b32 s1, 1
	v_ashrrev_i32_e32 v89, 31, v88
	v_mov_b32_e32 v93, 0xf149f2ca
	v_mov_b32_e32 v95, 0
	v_readlane_b32 s57, v252, 1
	v_readlane_b32 s58, v252, 2
	s_waitcnt vmcnt(5)
	ds_write_b128 v94, v[12:15] offset:9216
	s_waitcnt vmcnt(4)
	ds_write_b128 v94, v[16:19]
	v_mov_b32_e32 v14, v113
	v_mov_b32_e32 v15, v113
	v_mov_b32_e32 v12, v113
	v_mov_b32_e32 v13, v113
	v_mov_b64_e32 v[30:31], v[14:15]
	v_mov_b64_e32 v[28:29], v[12:13]
	v_mov_b64_e32 v[26:27], v[10:11]
	v_mov_b64_e32 v[24:25], v[8:9]
	v_mov_b64_e32 v[22:23], v[6:7]
	v_mov_b64_e32 v[20:21], v[4:5]
	v_mov_b64_e32 v[18:19], v[2:3]
	v_mov_b64_e32 v[16:17], v[0:1]
	v_readlane_b32 s59, v252, 3
	v_readlane_b32 s60, v252, 4
	v_readlane_b32 s61, v252, 5
	v_readlane_b32 s62, v252, 6
	v_readlane_b32 s63, v252, 7
	v_readlane_b32 s66, v252, 10
	v_readlane_b32 s67, v252, 11
	v_readlane_b32 s68, v252, 12
	v_readlane_b32 s69, v252, 13
	v_readlane_b32 s70, v252, 14
	v_readlane_b32 s71, v252, 15
	v_readlane_b32 s37, v252, 37
	v_readlane_b32 s40, v252, 40
	v_readlane_b32 s41, v252, 41
	v_readlane_b32 s42, v252, 42
	v_readlane_b32 s43, v252, 43
	s_waitcnt lgkmcnt(0)
	s_barrier
	s_branch .LBB0_586
; DI unsigned pk2(float a, float b) { f32x2 v = {a, b}; bf2_t r = __builtin_convertvector(v, bf2_t); return __builtin_bit_cast(unsigned, r); }
; DI f32x16 mfma32(bf16x8 a, bf16x8 b, f32x16 c) { return __builtin_amdgcn_mfma_f32_32x32x16_bf16(a, b, c, 0, 0, 0); }
; template <int MODE>
; DI void attn_unit(char* lds, const Params& p, int layer, int u) {
;     ...
;       { const f32x2 nm = {aoff - m, aoff - m};
; #pragma unroll
;         for (int r = 0; r < 8; ++r) {
;           f32x2 a = {S0[2 * r], S0[2 * r + 1]}, b = {S1[2 * r], S1[2 * r + 1]};
;           asm("v_pk_add_f32 %0, %1, %2" : "=v"(a) : "v"(a), "v"(nm));
;           asm("v_pk_add_f32 %0, %1, %2" : "=v"(b) : "v"(b), "v"(nm));
;           S0[2 * r] = a[0]; S0[2 * r + 1] = a[1]; S1[2 * r] = b[0]; S1[2 * r + 1] = b[1];
;         } }
; #pragma unroll
;       for (int r = 0; r < 16; ++r) { S0[r] = __builtin_amdgcn_exp2f(S0[r]); S1[r] = __builtin_amdgcn_exp2f(S1[r]); }
;       const f32x16 SS = S0 + S1;
;       float ps = 0.f;
; #pragma unroll
;       for (int r = 0; r < 16; ++r) ps += SS[r];
;       l += ps;
;       bf16x8 pf[4];
; #pragma unroll
;       for (int s = 0; s < 4; ++s) {
;         u32x4 w;
;         if (s < 2) { w[0] = pk2(S0[8 * s], S0[8 * s + 1]); w[1] = pk2(S0[8 * s + 2], S0[8 * s + 3]); w[2] = pk2(S0[8 * s + 4], S0[8 * s + 5]); w[3] = pk2(S0[8 * s + 6], S0[8 * s + 7]); }
;         else { const int s2 = s - 2; w[0] = pk2(S1[8 * s2], S1[8 * s2 + 1]); w[1] = pk2(S1[8 * s2 + 2], S1[8 * s2 + 3]); w[2] = pk2(S1[8 * s2 + 4], S1[8 * s2 + 5]); w[3] = pk2(S1[8 * s2 + 6], S1[8 * s2 + 7]); }
;         pf[s] = __builtin_bit_cast(bf16x8, w);
;       }
;       const char* vb = cur + VOFF + lr * VST + lh * 8;
; #pragma unroll
;       for (int s = 0; s < 4; ++s) {
;         { const s16x4 lo = *(const s16x4*)(vb + s * 32), hi = *(const s16x4*)(vb + s * 32 + 16);
;           O0 = mfma32(__builtin_shufflevector(lo, hi, 0, 1, 2, 3, 4, 5, 6, 7), pf[s], O0); }
;         { const s16x4 lo = *(const s16x4*)(vb + 32 * VST + s * 32), hi = *(const s16x4*)(vb + 32 * VST + s * 32 + 16);
;           O1 = mfma32(__builtin_shufflevector(lo, hi, 0, 1, 2, 3, 4, 5, 6, 7), pf[s], O1); }
;       }
;     }
;     __syncthreads();
.LBB0_585:
	v_sub_f32_e32 v90, 0, v93
	v_mov_b32_e32 v91, v90
	v_pk_add_f32 v[40:41], v[40:41], v[90:91]
	v_pk_add_f32 v[32:33], v[32:33], v[90:91]
	v_pk_add_f32 v[48:49], v[48:49], v[90:91]
	v_pk_add_f32 v[34:35], v[34:35], v[90:91]
	v_pk_add_f32 v[50:51], v[50:51], v[90:91]
	v_pk_add_f32 v[36:37], v[36:37], v[90:91]
	s_nop 3
	v_exp_f32_e32 v116, v40
	v_add_u32_e32 v40, v102, v112
	v_pk_add_f32 v[52:53], v[52:53], v[90:91]
	v_pk_add_f32 v[38:39], v[38:39], v[90:91]
	v_pk_add_f32 v[54:55], v[54:55], v[90:91]
	v_pk_add_f32 v[56:57], v[56:57], v[90:91]
	v_pk_add_f32 v[42:43], v[42:43], v[90:91]
	v_pk_add_f32 v[58:59], v[58:59], v[90:91]
	v_pk_add_f32 v[44:45], v[44:45], v[90:91]
	v_pk_add_f32 v[60:61], v[60:61], v[90:91]
	v_pk_add_f32 v[46:47], v[46:47], v[90:91]
	v_pk_add_f32 v[62:63], v[62:63], v[90:91]
	v_add_u32_e32 v91, 0x2000, v40
	v_exp_f32_e32 v104, v32
	v_exp_f32_e32 v105, v33
	v_exp_f32_e32 v106, v34
	v_exp_f32_e32 v107, v35
	ds_read2_b64 v[32:35], v91 offset0:128 offset1:130
	v_exp_f32_e32 v108, v36
	v_exp_f32_e32 v109, v37
	v_exp_f32_e32 v110, v38
	v_exp_f32_e32 v111, v39
	v_add_u32_e32 v114, 0x3000, v40
	v_exp_f32_e32 v117, v41
	v_exp_f32_e32 v118, v42
	v_exp_f32_e32 v119, v43
	ds_read2_b64 v[40:43], v114 offset0:192 offset1:194
	v_cvt_pk_bf16_f32 v36, v104, v105
	v_cvt_pk_bf16_f32 v37, v106, v107
	v_cvt_pk_bf16_f32 v38, v108, v109
	v_cvt_pk_bf16_f32 v39, v110, v111
	v_exp_f32_e32 v44, v44
	v_exp_f32_e32 v45, v45
	s_waitcnt lgkmcnt(1)
	v_mfma_f32_32x32x16_bf16 v[0:15], v[32:35], v[36:39], v[0:15]
	ds_read2_b64 v[32:35], v91 offset0:132 offset1:134
	v_exp_f32_e32 v46, v46
	v_exp_f32_e32 v47, v47
	v_exp_f32_e32 v48, v48
	v_exp_f32_e32 v49, v49
	v_exp_f32_e32 v50, v50
	v_exp_f32_e32 v51, v51
	s_waitcnt lgkmcnt(1)
	v_mfma_f32_32x32x16_bf16 v[16:31], v[40:43], v[36:39], v[16:31]
	ds_read2_b64 v[40:43], v114 offset0:196 offset1:198
	v_cvt_pk_bf16_f32 v36, v116, v117
	v_cvt_pk_bf16_f32 v37, v118, v119
	v_cvt_pk_bf16_f32 v38, v44, v45
	v_cvt_pk_bf16_f32 v39, v46, v47
	v_exp_f32_e32 v52, v52
	v_exp_f32_e32 v53, v53
	s_waitcnt lgkmcnt(1)
	v_mfma_f32_32x32x16_bf16 v[0:15], v[32:35], v[36:39], v[0:15]
	ds_read2_b64 v[32:35], v91 offset0:136 offset1:138
	v_exp_f32_e32 v54, v54
	v_exp_f32_e32 v55, v55
	v_pk_add_f32 v[104:105], v[104:105], v[48:49]
	v_pk_add_f32 v[106:107], v[106:107], v[50:51]
	v_add_f32_e32 v104, 0, v104
	v_pk_add_f32 v[108:109], v[108:109], v[52:53]
	s_waitcnt lgkmcnt(1)
	v_mfma_f32_32x32x16_bf16 v[16:31], v[40:43], v[36:39], v[16:31]
	ds_read2_b64 v[40:43], v114 offset0:200 offset1:202
	v_cvt_pk_bf16_f32 v36, v48, v49
	v_cvt_pk_bf16_f32 v37, v50, v51
	v_cvt_pk_bf16_f32 v38, v52, v53
	v_cvt_pk_bf16_f32 v39, v54, v55
	v_pk_add_f32 v[110:111], v[110:111], v[54:55]
	v_exp_f32_e32 v56, v56
	s_waitcnt lgkmcnt(1)
	v_mfma_f32_32x32x16_bf16 v[0:15], v[32:35], v[36:39], v[0:15]
	v_add_f32_e32 v32, v105, v104
	v_add_f32_e32 v32, v106, v32
	v_add_f32_e32 v32, v107, v32
	v_add_f32_e32 v32, v108, v32
	v_add_f32_e32 v32, v109, v32
	v_add_f32_e32 v48, v110, v32
	ds_read2_b64 v[32:35], v91 offset0:140 offset1:142
	s_waitcnt lgkmcnt(1)
	v_mfma_f32_32x32x16_bf16 v[16:31], v[40:43], v[36:39], v[16:31]
	ds_read2_b64 v[40:43], v114 offset0:204 offset1:206
	v_exp_f32_e32 v57, v57
	v_exp_f32_e32 v58, v58
	v_exp_f32_e32 v59, v59
	v_exp_f32_e32 v60, v60
	v_exp_f32_e32 v62, v62
	v_exp_f32_e32 v63, v63
	v_exp_f32_e32 v61, v61
	v_pk_add_f32 v[116:117], v[116:117], v[56:57]
	v_add_f32_e32 v36, v111, v48
	v_add_f32_e32 v48, v116, v36
	v_cvt_pk_bf16_f32 v36, v56, v57
	v_cvt_pk_bf16_f32 v37, v58, v59
	v_cvt_pk_bf16_f32 v38, v60, v61
	v_cvt_pk_bf16_f32 v39, v62, v63
	v_pk_add_f32 v[102:103], v[46:47], v[62:63]
	v_pk_add_f32 v[46:47], v[118:119], v[58:59]
	s_waitcnt lgkmcnt(1)
	v_mfma_f32_32x32x16_bf16 v[0:15], v[32:35], v[36:39], v[0:15]
	v_add_f32_e32 v32, v117, v48
	v_add_f32_e32 v32, v46, v32
	v_add_f32_e64 v44, v44, v60
	v_add_f32_e64 v45, v45, v61
	v_add_f32_e32 v32, v47, v32
	v_add_f32_e32 v32, v44, v32
	v_add_f32_e32 v32, v45, v32
	v_add_f32_e32 v32, v102, v32
	s_waitcnt lgkmcnt(0)
	v_mfma_f32_32x32x16_bf16 v[16:31], v[40:43], v[36:39], v[16:31]
	v_add_f32_e32 v32, v103, v32
	s_add_i32 s1, s1, 1
	v_add_f32_e32 v95, v95, v32
	v_add_u32_e32 v101, 64, v101
	s_cmp_eq_u32 s1, 63
	v_lshl_add_u64 v[98:99], v[98:99], 0, s[8:9]
	s_barrier
	s_cbranch_scc1 .LBB0_588
; template <int MODE>
; DI void attn_unit(char* lds, const Params& p, int layer, int u) {
;     ...
;     char* cur = lds + (t & 1) * BUFSZ;
;     if (t + 1 < NT) { stage(lds + ((t + 1) & 1) * BUFSZ); if (t + 2 < NT) prefetch(t + 2); }
;     const int key0 = (MODE == 3) ? q0 - 64 + 64 * t : 64 * (tlo + t);
;     const bool act = (MODE != 3) || (t >= (wid >> 1) && t <= (wid >> 1) + 2);
;     if (act) {
;       f32x16 S0 = zero16(), S1 = zero16();
;       const char* kb = cur + lr * KST + (MODE == 0 ? comp * 64 : 0) + lh * 16;
; #pragma unroll
;       for (int ks = 0; ks < NKS; ++ks) {
;         const bf16x8 k0 = *(const bf16x8*)(kb + ks * 32), k1 = *(const bf16x8*)(kb + 32 * KST + ks * 32);
;         S0 = mfma32(k0, qf[ks], S0); S1 = mfma32(k1, qf[ks], S1);
;       }
;       float aoff = 0.f;
;       if (MODE == 0) {
;         const float dbase = (float)(key0 + 4 * lh - qrow);
;         if (key0 > qlo + 31) { S0 = S0 - T0; S1 = S1 - T1; aoff = -slope2 * dbase; }
;         else if (key0 + 63 < qlo) { S0 = S0 + T0; S1 = S1 + T1; aoff = slope2 * dbase; }
;         else {
; #pragma unroll
;           for (int r = 0; r < 16; ++r) { const float cc = (float)((r & 3) + 8 * (r >> 2));
;             S0[r] = fmaf(-slope2, fabsf(dbase + cc), S0[r]); S1[r] = fmaf(-slope2, fabsf(dbase + cc + 32.f), S1[r]); }
;         }
;       }
;       if (MODE == 3) {
;         const int rel0 = key0 + 4 * lh - qrow;
; #pragma unroll
;         for (int r = 0; r < 16; ++r) { const int cc = (r & 3) + 8 * (r >> 2);
;           { const int rel = rel0 + cc, v = qrow + rel; const bool ok = (rel >= -64) && (rel <= 64) && (v >= 0) && (v < L); S0[r] = ok ? fmaf(-slope2, fabsf((float)rel), S0[r]) : -1e30f; }
;           { const int rel = rel0 + cc + 32, v = qrow + rel; const bool ok = (rel >= -64) && (rel <= 64) && (v >= 0) && (v < L); S1[r] = ok ? fmaf(-slope2, fabsf((float)rel), S1[r]) : -1e30f; } }
;       }
;       float mx = fmaxf(S0[0], S1[0]);
; #pragma unroll
;       for (int r = 1; r < 16; ++r) mx = max3f(mx, S0[r], S1[r]);
;       mx += aoff;
;       if (__any(mx > m + 8.f)) {
;         mx = fmaxf(mx, __shfl_xor(mx, 32));
;         const float mnew = fmaxf(m, mx);
;         const float al = __builtin_amdgcn_exp2f(m - mnew); l *= al; O0 *= al; O1 *= al;
;         m = mnew;
;       }
.LBB0_586:
	s_bitcmp1_b32 s1, 0
	s_cselect_b32 s4, 0, 0x4800
	s_cselect_b32 s33, 0x4800, 0
	v_add_u32_e32 v32, s33, v94
	v_add_u32_e32 v102, s4, v100
	s_waitcnt vmcnt(1)
	ds_write_b128 v32, v[84:87]
	s_waitcnt vmcnt(0)
	ds_write_b128 v32, v[80:83] offset:9216
	v_add_u32_e32 v90, v102, v92
	ds_read_b128 v[32:35], v90
	ds_read_b128 v[104:107], v90 offset:32
	v_mad_i64_i32 v[80:81], s[50:51], v101, s72, v[96:97]
	ds_read_b128 v[48:51], v90 offset:4608
	global_load_dwordx4 v[84:87], v[80:81], off offset:3328
	s_nop 0
	global_load_dwordx4 v[80:83], v[98:99], off
	s_waitcnt lgkmcnt(2)
	v_mfma_f32_32x32x16_bf16 v[32:47], v[32:35], v[76:79], 0
	s_waitcnt lgkmcnt(1)
	v_mfma_f32_32x32x16_bf16 v[32:47], v[104:107], v[72:75], v[32:47]
	ds_read_b128 v[104:107], v90 offset:4640
	s_waitcnt lgkmcnt(1)
	v_mfma_f32_32x32x16_bf16 v[48:63], v[48:51], v[76:79], 0
	s_waitcnt lgkmcnt(0)
	v_mfma_f32_32x32x16_bf16 v[48:63], v[104:107], v[72:75], v[48:63]
	ds_read_b128 v[104:107], v90 offset:64
	s_waitcnt lgkmcnt(0)
	v_mfma_f32_32x32x16_bf16 v[32:47], v[104:107], v[68:71], v[32:47]
	ds_read_b128 v[104:107], v90 offset:4672
	s_waitcnt lgkmcnt(0)
	v_mfma_f32_32x32x16_bf16 v[48:63], v[104:107], v[68:71], v[48:63]
	ds_read_b128 v[104:107], v90 offset:4704
	s_waitcnt lgkmcnt(0)
	v_mfma_f32_32x32x16_bf16 v[48:63], v[104:107], v[64:67], v[48:63]
	ds_read_b128 v[104:107], v90 offset:96
	s_waitcnt lgkmcnt(0)
	v_mfma_f32_32x32x16_bf16 v[32:47], v[104:107], v[64:67], v[32:47]
	s_nop 8
	v_max_f32_e32 v90, v48, v48
	s_nop 1
	v_max_f32_e32 v91, v32, v32
	v_max_f32_e32 v90, v91, v90
	v_max3_f32 v90, v90, v33, v49
	v_add_f32_e32 v91, 0x41000000, v93
	v_max3_f32 v90, v90, v34, v50
	s_nop 0
	v_max3_f32 v90, v90, v35, v51
	s_nop 0
	v_max3_f32 v90, v90, v36, v52
	s_nop 0
	v_max3_f32 v90, v90, v37, v53
	s_nop 0
	v_max3_f32 v90, v90, v38, v54
	s_nop 0
	v_max3_f32 v90, v90, v39, v55
	s_nop 0
	v_max3_f32 v90, v90, v40, v56
	s_nop 0
	v_max3_f32 v90, v90, v41, v57
	s_nop 0
	v_max3_f32 v90, v90, v42, v58
	s_nop 0
	v_max3_f32 v90, v90, v43, v59
	s_nop 0
	v_max3_f32 v90, v90, v44, v60
	s_nop 0
	v_max3_f32 v90, v90, v45, v61
	s_nop 0
	v_max3_f32 v90, v90, v46, v62
	s_nop 0
	v_max3_f32 v90, v90, v47, v63
	s_nop 0
	v_cmp_gt_f32_e32 vcc, v90, v91
	s_cbranch_vccz .LBB0_585
	v_cmp_lt_i32_e32 vcc, v209, v208
	v_add_f32_e32 v90, 0, v90
	s_nop 0
	v_cndmask_b32_e32 v91, v207, v209, vcc
	v_lshlrev_b32_e32 v91, 2, v91
	ds_bpermute_b32 v91, v91, v90
	s_waitcnt lgkmcnt(0)
	v_max3_f32 v91, v93, v90, v91
	v_sub_f32_e32 v90, v93, v91
	v_exp_f32_e32 v90, v90
	v_mov_b32_e32 v93, v91
	v_mul_f32_e32 v95, v95, v90
	v_pk_mul_f32 v[14:15], v[14:15], v[90:91] op_sel_hi:[1,0]
	v_pk_mul_f32 v[12:13], v[12:13], v[90:91] op_sel_hi:[1,0]
	v_pk_mul_f32 v[10:11], v[10:11], v[90:91] op_sel_hi:[1,0]
	v_pk_mul_f32 v[8:9], v[8:9], v[90:91] op_sel_hi:[1,0]
	v_pk_mul_f32 v[6:7], v[6:7], v[90:91] op_sel_hi:[1,0]
	v_pk_mul_f32 v[4:5], v[4:5], v[90:91] op_sel_hi:[1,0]
	v_pk_mul_f32 v[2:3], v[2:3], v[90:91] op_sel_hi:[1,0]
	v_pk_mul_f32 v[0:1], v[0:1], v[90:91] op_sel_hi:[1,0]
	v_pk_mul_f32 v[30:31], v[30:31], v[90:91] op_sel_hi:[1,0]
	v_pk_mul_f32 v[28:29], v[28:29], v[90:91] op_sel_hi:[1,0]
	v_pk_mul_f32 v[26:27], v[26:27], v[90:91] op_sel_hi:[1,0]
	v_pk_mul_f32 v[24:25], v[24:25], v[90:91] op_sel_hi:[1,0]
	v_pk_mul_f32 v[22:23], v[22:23], v[90:91] op_sel_hi:[1,0]
	v_pk_mul_f32 v[20:21], v[20:21], v[90:91] op_sel_hi:[1,0]
	v_pk_mul_f32 v[18:19], v[18:19], v[90:91] op_sel_hi:[1,0]
	v_pk_mul_f32 v[16:17], v[16:17], v[90:91] op_sel_hi:[1,0]
	s_branch .LBB0_585
